# scan phase: static s_setprio 1 for the two MFMA-stage waves (0,1), reset at phase end
# speedup vs baseline: 1.0160x; 1.0160x over previous
.LBB0_391:
	s_andn2_b64 vcc, exec, s[0:1]
	s_cbranch_vccnz .LBB0_471
	v_readlane_b32 s0, v252, 25
	v_mov_b32_e32 v115, v228
	v_readlane_b32 s1, v252, 26
	s_andn2_b64 vcc, exec, s[0:1]
	v_readfirstlane_b32 s0, v115
	s_cbranch_vccnz .LBB0_416
	s_ashr_i32 s2, s0, 6
	v_bfe_u32 v7, v115, 4, 2
	v_lshl_or_b32 v130, s2, 2, v7
	s_cmp_lt_i32 s2, 4
	v_cmp_lt_i32_e32 vcc, s33, v130
	s_cselect_b64 s[40:41], -1, 0
	s_lshl_b32 s3, s2, 4
	v_cndmask_b32_e32 v7, v207, v208, vcc
	s_cmp_lt_i32 s2, 2
	v_sub_u32_e32 v131, v7, v130
	v_bfe_u32 v7, v115, 3, 3
	s_cselect_b64 s[14:15], -1, 0
	s_cbranch_scc0 .Lsp_skip
	s_setprio 1
.Lsp_skip:
	s_cmp_gt_i32 s2, 1
	v_and_b32_e32 v4, 31, v115
	s_mul_i32 s26, s2, 0x410
	v_lshl_or_b32 v132, s2, 3, v7
	s_mul_i32 s6, s2, 0x420
	s_cselect_b64 s[12:13], -1, 0
	s_lshl_b32 s8, s2, 5
	s_lshl_b32 s7, s2, 12
	s_add_i32 s10, s2, -2
	s_lshl_b32 s2, s2, 11
	v_ashrrev_i32_e32 v1, 2, v115
	v_and_b32_e32 v0, 63, v115
	v_lshlrev_b32_e32 v11, 6, v4
	s_add_i32 s2, s2, 0x10400
	v_lshlrev_b32_e32 v128, 1, v1
	v_lshl_or_b32 v129, v0, 2, v206
	v_and_b32_e32 v0, 0x7ffffff0, v1
	v_cmp_lt_i32_e32 vcc, s33, v132
	v_lshlrev_b32_e32 v138, 8, v4
	v_add_u32_e32 v140, s2, v11
	s_movk_i32 s2, 0xff40
	v_and_or_b32 v5, v128, 8, v0
	v_and_b32_e32 v6, 3, v115
	v_cndmask_b32_e32 v7, v207, v208, vcc
	v_mad_i32_i24 v142, v4, s2, v138
	s_movk_i32 s2, 0x11ff
	v_sub_u32_e32 v133, v7, v132
	v_lshlrev_b32_e32 v7, 3, v6
	v_lshrrev_b32_e32 v5, 3, v5
	v_bitop3_b32 v144, v4, s2, v209 bitop3:0x36
	s_movk_i32 s2, 0x820
	v_cmp_eq_u32_e64 s[0:1], 0, v6
	v_cmp_lt_u32_e64 s[38:39], 1, v6
	v_and_b32_e32 v8, 8, v1
	v_mul_u32_u24_e32 v137, 0x420, v6
	s_lshl_b32 s11, s10, 11
	v_mad_u32_u24 v145, v6, s2, v128
	v_lshlrev_b32_e32 v6, 11, v6
	v_bitop3_b32 v21, v5, v7, 8 bitop3:0x78
	v_and_or_b32 v8, v128, 6, v8
	s_add_i32 s11, s11, 0x10400
	v_or_b32_e32 v14, 4, v7
	v_lshl_add_u32 v6, v21, 4, v6
	v_bfe_u32 v3, v115, 5, 1
	v_add_u32_e32 v12, s11, v11
	v_lshrrev_b32_e32 v15, 2, v14
	s_movk_i32 s2, 0x410
	v_or_b32_e32 v147, v6, v8
	v_or_b32_e32 v6, 1, v7
	v_lshl_or_b32 v139, v3, 3, v12
	v_or_b32_e32 v11, 2, v7
	v_or_b32_e32 v12, 3, v7
	v_mad_u32_u24 v146, v15, s2, v128
	v_or_b32_e32 v15, 5, v7
	v_or_b32_e32 v17, 6, v7
	v_or_b32_e32 v19, 7, v7
	v_lshlrev_b32_e32 v7, 8, v6
	v_bitop3_b32 v6, v5, v6, 9 bitop3:0x78
	v_lshl_add_u32 v6, v6, 4, v7
	v_or_b32_e32 v148, v6, v8
	v_lshlrev_b32_e32 v6, 8, v11
	v_bitop3_b32 v7, v5, v11, 10 bitop3:0x78
	v_lshl_add_u32 v6, v7, 4, v6
	v_or_b32_e32 v149, v6, v8
	v_lshlrev_b32_e32 v6, 8, v12
	v_bitop3_b32 v7, v5, v12, 11 bitop3:0x78
	v_lshl_add_u32 v6, v7, 4, v6
	v_or_b32_e32 v150, v6, v8
	v_lshlrev_b32_e32 v6, 8, v14
	v_bitop3_b32 v7, v5, v14, 12 bitop3:0x78
	v_lshl_add_u32 v6, v7, 4, v6
	v_or_b32_e32 v151, v6, v8
	v_lshlrev_b32_e32 v6, 8, v15
	v_bitop3_b32 v7, v5, v15, 13 bitop3:0x78
	v_lshl_add_u32 v6, v7, 4, v6
	v_or_b32_e32 v152, v6, v8
	v_lshlrev_b32_e32 v6, 8, v17
	v_bitop3_b32 v7, v5, v17, 14 bitop3:0x78
	v_lshl_add_u32 v6, v7, 4, v6
	v_or_b32_e32 v153, v6, v8
	v_lshlrev_b32_e32 v6, 8, v19
	v_bitop3_b32 v5, v5, v19, 15 bitop3:0x78
	v_lshl_add_u32 v5, v5, 4, v6
	v_lshlrev_b32_e32 v114, 2, v3
	v_and_b32_e32 v13, 15, v115
	v_or_b32_e32 v154, v5, v8
	v_bitop3_b32 v5, v3, v115, 15 bitop3:0x78
	v_lshlrev_b32_e32 v155, 4, v5
	v_bitop3_b32 v5, v3, v13, 2 bitop3:0x36
	v_or_b32_e32 v8, 3, v114
	v_or_b32_e32 v11, 2, v114
	v_lshlrev_b32_e32 v156, 4, v5
	v_bitop3_b32 v5, v3, v13, 4 bitop3:0x36
	v_cmp_gt_u32_e64 s[48:49], v8, v4
	v_cmp_gt_u32_e64 s[50:51], v11, v4
	v_or_b32_e32 v8, 9, v114
	v_or_b32_e32 v11, 8, v114
	v_lshlrev_b32_e32 v157, 4, v5
	v_bitop3_b32 v5, v3, v13, 6 bitop3:0x36
	v_cmp_gt_u32_e64 s[52:53], v8, v4
	v_cmp_gt_u32_e64 s[54:55], v11, v4
	v_or_b32_e32 v8, 11, v114
	v_or_b32_e32 v11, 10, v114
	v_lshlrev_b32_e32 v158, 4, v5
	v_bitop3_b32 v5, v3, v13, 8 bitop3:0x36
	v_cmp_gt_u32_e64 s[56:57], v8, v4
	v_cmp_gt_u32_e64 s[58:59], v11, v4
	v_or_b32_e32 v8, 17, v114
	v_or_b32_e32 v11, 16, v114
	v_lshlrev_b32_e32 v159, 4, v5
	v_bitop3_b32 v5, v3, v13, 10 bitop3:0x36
	v_cmp_gt_u32_e64 s[60:61], v8, v4
	v_cmp_gt_u32_e64 s[62:63], v11, v4
	v_or_b32_e32 v8, 19, v114
	v_or_b32_e32 v11, 18, v114
	v_lshlrev_b32_e32 v2, 3, v115
	v_bfe_u32 v10, v115, 2, 2
	v_lshlrev_b32_e32 v160, 4, v5
	v_bitop3_b32 v5, v3, v13, 12 bitop3:0x36
	v_cmp_gt_u32_e64 s[64:65], v8, v4
	v_cmp_gt_u32_e64 s[66:67], v11, v4
	v_or_b32_e32 v8, 25, v114
	v_or_b32_e32 v11, 24, v114
	v_and_b32_e32 v0, 0x78, v2
	v_lshlrev_b32_e32 v135, 6, v1
	v_lshlrev_b32_e32 v1, 4, v115
	v_lshrrev_b32_e32 v9, 2, v115
	v_lshrrev_b32_e32 v16, 2, v15
	v_lshrrev_b32_e32 v18, 2, v17
	v_lshrrev_b32_e32 v20, 2, v19
	v_lshlrev_b32_e32 v161, 4, v5
	v_bitop3_b32 v5, v3, v13, 14 bitop3:0x36
	v_lshlrev_b32_e32 v163, 4, v10
	v_cmp_gt_u32_e64 s[68:69], v8, v4
	v_cmp_gt_u32_e64 s[70:71], v11, v4
	v_or_b32_e32 v8, 27, v114
	v_or_b32_e32 v11, 26, v114
	v_lshlrev_b32_e32 v176, 1, v0
	v_and_b32_e32 v2, 56, v2
	v_or_b32_e32 v134, 0xffffffe0, v115
	v_bitop3_b32 v136, v1, 48, v115 bitop3:0x48
	v_add_u32_e32 v1, 0x10400, v135
	v_lshlrev_b32_e32 v141, 4, v3
	v_or_b32_e32 v254, 0x11400, v141
	v_or_b32_e32 v143, 0x10e0, v4
	v_lshlrev_b32_e32 v162, 4, v5
	v_xor_b32_e32 v5, 16, v163
	v_xor_b32_e32 v6, 32, v163
	v_xor_b32_e32 v7, 48, v163
	v_cmp_gt_u32_e64 s[44:45], v114, v4
	v_cmp_lt_u32_e64 s[46:47], v114, v4
	v_cmp_gt_u32_e64 s[72:73], v8, v4
	v_cmp_gt_u32_e64 s[74:75], v11, v4
	v_bitop3_b32 v4, v3, v9, 3 bitop3:0x78
	v_bitop3_b32 v3, v3, v10, 2 bitop3:0x36
	v_mad_u32_u24 v166, v16, s2, v128
	v_mad_u32_u24 v167, v18, s2, v128
	v_mad_u32_u24 v168, v20, s2, v128
	s_add_i32 s88, s26, s3
	v_readlane_b32 s2, v252, 52
	v_lshl_add_u64 v[112:113], s[86:87], 0, v[176:177]
	v_cmp_gt_i32_e64 s[42:43], s27, v115
	s_ashr_i32 s9, s8, 31
	s_lshl_b32 s10, s10, 12
	v_lshlrev_b32_e32 v164, 4, v4
	v_lshlrev_b32_e32 v165, 4, v3
	v_sub_u32_e32 v169, 0, v134
	v_add_u32_e32 v170, 32, v132
	v_sub_u32_e32 v171, 0xffffffe0, v132
	v_add_u32_e32 v172, 32, v130
	v_sub_u32_e32 v173, 0xffffffe0, v130
	v_lshlrev_b32_e32 v176, 1, v0
	v_lshlrev_b32_e32 v116, 1, v2
	s_add_i32 s11, s26, 0x2080
	s_addk_i32 s88, 0x4100
	v_add_u32_e32 v174, v1, v136
	v_add_u32_e32 v175, v139, v5
	v_add_u32_e32 v178, v139, v6
	v_add_u32_e32 v179, v139, v7
	s_mov_b32 s89, s2
	v_readlane_b32 s3, v252, 53
	s_branch .LBB0_395

.LBB0_416:
	s_setprio 0
	s_add_i32 s6, s84, 4
	s_cmp_ge_i32 s6, s31
	s_cbranch_scc1 .LBB0_428
	s_waitcnt vmcnt(0)
	s_barrier
	s_mov_b64 s[0:1], exec
	v_readlane_b32 s2, v253, 0
	v_readlane_b32 s3, v253, 1
	v_readlane_b32 s68, v251, 28
	v_readlane_b32 s34, v251, 2
	v_readlane_b32 s54, v251, 4
	v_readlane_b32 s22, v251, 6
	v_readlane_b32 s92, v251, 8
	v_readlane_b32 s56, v251, 10
	v_readlane_b32 s58, v251, 12
	v_readlane_b32 s60, v251, 14
	v_readlane_b32 s62, v251, 16
	v_readlane_b32 s64, v251, 18
	v_readlane_b32 s66, v251, 20
	v_readlane_b32 s76, v251, 22
	v_readlane_b32 s88, v251, 24
	v_readlane_b32 s82, v251, 26
	s_and_b64 s[2:3], s[0:1], s[2:3]
	v_readlane_b32 s69, v251, 29
	v_readlane_b32 s70, v251, 30
	v_readlane_b32 s71, v251, 31
	v_readlane_b32 s72, v251, 32
	v_readlane_b32 s73, v251, 33
	v_readlane_b32 s74, v251, 34
	v_readlane_b32 s75, v251, 35
	v_readlane_b32 s35, v251, 3
	v_readlane_b32 s55, v251, 5
	v_readlane_b32 s23, v251, 7
	v_readlane_b32 s93, v251, 9
	v_readlane_b32 s57, v251, 11
	v_readlane_b32 s59, v251, 13
	v_readlane_b32 s61, v251, 15
	v_readlane_b32 s63, v251, 17
	v_readlane_b32 s65, v251, 19
	v_readlane_b32 s67, v251, 21
	v_readlane_b32 s77, v251, 23
	v_readlane_b32 s89, v251, 25
	v_readlane_b32 s83, v251, 27
	s_mov_b64 exec, s[2:3]
	s_cbranch_execz .LBB0_470
	s_waitcnt vmcnt(0) expcnt(0) lgkmcnt(0)
	ds_read_b32 v2, v202
	ds_read_b32 v0, v203
	s_waitcnt lgkmcnt(1)
	v_cmp_ne_u32_e32 vcc, 0, v2
	s_cbranch_vccnz .LBB0_434
	v_readlane_b32 s8, v253, 36
	v_readlane_b32 s9, v253, 37
	s_load_dwordx2 s[2:3], s[8:9], 0x0
	s_load_dword s7, s[8:9], 0x8
	s_mov_b32 s10, 1
	s_waitcnt lgkmcnt(0)
	s_mul_i32 s2, s3, s2
	s_mul_i32 s7, s2, s7
	s_branch .LBB0_421
